# XCD-staggered start (XCD g sleeps g*1.2us) before the MLP up-projection GEMM phase so the XCDs' epilogue store bursts do not coincide
# baseline (speedup 1.0000x reference)
; #define PG8_STAGE(bufoff, gbase, voff) do { _Pragma("unroll") for (int _i = 0; _i < 2; ++_i) \
;         __builtin_amdgcn_global_load_lds((const unsigned*)((const char*)(gbase) + (voff)[_i]), (LAS unsigned*)(lds + (bufoff) + ldsw + _i * 8192), 16, 0, 0); } while (0)
; #define PG8_BAR __builtin_amdgcn_s_barrier()
; template <class Epi, class Map>
; __device__ __forceinline__ void gemm_phase(LAS unsigned char* lds, const Gemm g, const Sched<Map>& S, const Epi& E) {
;     ...
;     const int tid = tid_, wid = __builtin_amdgcn_readfirstlane(tid >> 6), lane = tid & 63, wr = wid >> 2, wc = wid & 3, fr = lane & 15, fq = lane >> 4;
;     const int K = g.K, nt = K / BK;
;     unsigned voffA[2], voffB[2];
; #pragma unroll
;     for (int i = 0; i < 2; ++i) { int R, C; stage_rc(tid * 16 + i * 8192, R, C); const int Rb = Epi::PERM ? ((R & ~31) + perm32(R & 31)) : R;
;         voffA[i] = (unsigned)(R * g.lda + C) * 2u; voffB[i] = (unsigned)(Rb * g.ldb + C) * 2u; }
;     const size_t kstep = (size_t)(BK * 2);
;     const size_t hstepA = (size_t)HALF * g.lda * 2, hstepB = (size_t)HALF * g.ldb * 2;
;     const unsigned ldsw = (unsigned)wid * 1024u;
;     const int aoff = lds_byte(wr * 64 + fr, fq * 8), boff = lds_byte(wc * 32 + fr, fq * 8);
;     ...
;     Unit cur, nxt; int ui = 0;
;     if (!S.next(0, cur)) return;
;     f32x4 acc[2][2][4][2];
; #pragma unroll
;     for (int a = 0; a < 2; ++a)
; #pragma unroll
;         for (int b = 0; b < 2; ++b)
; #pragma unroll
;             for (int m = 0; m < 4; ++m)
; #pragma unroll
;                 for (int n = 0; n < 2; ++n) acc[a][b][m][n] = (f32x4){0.f, 0.f, 0.f, 0.f};
;     bf16x8 At[4][2], B0[2][2], B1[2][2];
;     const char* cA = (const char*)g.A + cur.aoff; const char* cB = (const char*)g.Bt + cur.boff;
;     PG8_STAGE(PG8_SB(0, 0), cB, voffB); PG8_STAGE(PG8_SB(0, 1), cB + hstepB, voffB); PG8_STAGE(PG8_SA(0, 0), cA, voffA); PG8_STAGE(PG8_SA(0, 1), cA + hstepA, voffA);
;     if (wr == 1) PG8_BAR;
;     PG8_WAIT_V(2); PG8_BAR;
;     PG8_STAGE(PG8_SB(1, 0), cB + kstep, voffB); PG8_STAGE(PG8_SA(1, 0), cA + kstep, voffA); PG8_STAGE(PG8_SB(1, 1), cB + hstepB + kstep, voffB);
; __global__ void __launch_bounds__(NT, 2) fwd_megakernel(Args a) {
;     ...
;         SYNC();
;         { Gemm g{H, Wt + (layer == 0 ? W0_1 : W1_1), D, D, D}; auto S = mk_sched(128, 32, MapMlp1{});
;           EpiBf16<2> E{ACT, DFF}; gemm_phase(X.lds, g, S, E);
.LBB0_1075:
	s_or_b64 exec, exec, s[16:17]
	v_readlane_b32 s0, v247, 46
	s_waitcnt vmcnt(22)
	v_mov_b32_e32 v6, v182
	v_readlane_b32 s1, v247, 47
	s_waitcnt lgkmcnt(0)
	s_barrier
	s_and_b32 m0, s77, 7
	s_cmp_eq_u32 m0, 0
	s_cbranch_scc1 .Lstag_done_mlp1
.Lstag_loop_mlp1:
	s_sleep 37
	s_sub_u32 m0, m0, 1
	s_cmp_lg_u32 m0, 0
	s_cbranch_scc1 .Lstag_loop_mlp1
.Lstag_done_mlp1:
	s_andn2_b64 vcc, exec, s[0:1]
	v_readfirstlane_b32 s8, v6
	s_cbranch_vccnz .LBB0_1095
	s_waitcnt vmcnt(8)
	v_lshlrev_b32_e32 v3, 4, v6
	v_add_u32_e32 v1, 0x2000, v3
	v_ashrrev_i32_e32 v0, 31, v1
	v_lshrrev_b32_e32 v0, 22, v0
	v_add_u32_e32 v0, v1, v0
	v_ashrrev_i32_e32 v0, 10, v0
	v_mul_i32_i24_e32 v2, 0x400, v0
	v_sub_u32_e32 v1, v1, v2
	v_lshrrev_b32_e32 v2, 4, v1
	v_bitop3_b32 v2, v2, v1, 32 bitop3:0x6c
	v_ashrrev_i32_e32 v1, 31, v2
	v_lshrrev_b32_e32 v1, 26, v1
	v_add_u32_e32 v4, v2, v1
	v_lshlrev_b32_e32 v5, 3, v0
	v_ashrrev_i32_e32 v1, 6, v4
	v_and_b32_e32 v5, -16, v5
	v_add_u32_e32 v5, v1, v5
	v_and_b32_e32 v7, 3, v1
	s_mov_b32 s1, 0xfffe0
	v_lshrrev_b32_e32 v8, 2, v5
	v_lshlrev_b32_e32 v9, 1, v5
	v_and_b32_e32 v4, 0xc0, v4
	v_and_or_b32 v7, v5, s1, v7
	v_and_b32_e32 v8, 4, v8
	v_and_b32_e32 v9, 24, v9
	v_sub_u32_e32 v2, v2, v4
	v_or3_b32 v7, v7, v8, v9
	v_lshlrev_b32_e32 v8, 5, v0
	v_ashrrev_i16_sdwa v2, v184, sext(v2) dst_sel:DWORD dst_unused:UNUSED_PAD src0_sel:DWORD src1_sel:BYTE_0
	v_and_b32_e32 v8, 32, v8
	v_bfe_i32 v2, v2, 0, 16
	v_add_lshl_u32 v4, v8, v2, 1
	v_lshl_add_u32 v128, v7, 12, v4
	v_lshl_add_u32 v130, v5, 12, v4
	v_bfe_i32 v4, v6, 27, 1
	v_lshrrev_b32_e32 v4, 22, v4
	v_add_u32_e32 v4, v3, v4
	v_and_b32_e32 v4, 0xfffffc00, v4
	v_sub_u32_e32 v3, v3, v4
	v_lshrrev_b32_e32 v4, 4, v3
	v_bitop3_b32 v5, v4, v3, 32 bitop3:0x6c
	v_ashrrev_i32_e32 v4, 31, v6
	v_lshrrev_b32_e32 v4, 26, v4
	v_ashrrev_i32_e32 v3, 31, v5
	v_add_u32_e32 v4, v6, v4
	v_lshrrev_b32_e32 v3, 26, v3
	v_ashrrev_i32_e32 v4, 6, v4
	v_add_u32_e32 v7, v5, v3
	v_lshlrev_b32_e32 v8, 3, v4
	v_ashrrev_i32_e32 v3, 6, v7
	v_and_b32_e32 v8, -16, v8
	v_add_u32_e32 v8, v3, v8
	v_and_b32_e32 v9, 3, v3
	v_lshrrev_b32_e32 v10, 2, v8
	v_lshlrev_b32_e32 v11, 1, v8
	v_and_b32_e32 v7, 0xc0, v7
	s_ashr_i32 s6, s8, 6
	v_and_or_b32 v9, v8, s1, v9
	v_and_b32_e32 v10, 4, v10
	v_and_b32_e32 v11, 24, v11
	v_sub_u32_e32 v5, v5, v7
	s_ashr_i32 s7, s8, 8
	s_lshl_b32 s0, s6, 10
	v_or3_b32 v9, v9, v10, v11
	v_lshlrev_b32_e32 v10, 5, v4
	v_ashrrev_i16_sdwa v5, v184, sext(v5) dst_sel:DWORD dst_unused:UNUSED_PAD src0_sel:DWORD src1_sel:BYTE_0
	v_readlane_b32 s1, v245, 20
	v_readlane_b32 s2, v244, 20
	v_and_b32_e32 v10, 32, v10
	v_bfe_i32 v5, v5, 0, 16
	s_add_u32 s34, s2, s1
	v_readlane_b32 s1, v244, 21
	v_add_lshl_u32 v7, v10, v5, 1
	s_addc_u32 s35, s1, 0
	s_add_i32 s1, s0, 0
	v_lshl_add_u32 v144, v9, 12, v7
	s_add_i32 m0, s1, 0x10000
	v_readlane_b32 s4, v245, 23
	global_load_lds_dwordx4 v144, s[34:35]
	s_add_i32 m0, s1, 0x12000
	s_add_u32 s2, s34, 0x80000
	global_load_lds_dwordx4 v128, s[34:35]
	s_addc_u32 s3, s35, 0
	s_add_i32 m0, s1, 0x14000
	v_lshl_add_u32 v132, v8, 12, v7
	global_load_lds_dwordx4 v144, s[2:3]
	s_add_i32 m0, s1, 0x16000
	v_readlane_b32 s5, v245, 24
	global_load_lds_dwordx4 v128, s[2:3]
	s_mov_b32 m0, s1
	s_add_i32 s2, s1, 0x2000
	s_add_i32 s3, s1, 0x4000
	s_nop 0
	global_load_lds_dwordx4 v132, s[4:5]
	s_mov_b32 m0, s2
	v_readlane_b32 s10, v245, 25
	global_load_lds_dwordx4 v130, s[4:5]
	s_mov_b32 m0, s3
	v_readlane_b32 s11, v245, 26
	s_add_i32 s4, s1, 0x6000
	s_cmp_eq_u32 s7, 1
	s_cselect_b64 s[16:17], -1, 0
	s_cmp_lg_u32 s7, 1
	s_nop 0
	global_load_lds_dwordx4 v132, s[10:11]
	s_mov_b32 m0, s4
	s_nop 0
	global_load_lds_dwordx4 v130, s[10:11]
	s_cbranch_scc1 .LBB0_1078
	s_barrier
